# v35 + removed the unneeded MFMA-to-VALU s_nop 8 pad at the head of the two deferred softmax+PV copies (waves 4-7, no MFMA precedes there)
# speedup vs baseline: 1.0087x; 1.0087x over previous
; template <int DQK, bool CAUSAL, bool ROPE> ...
;     ...
;         if (grp == 1 && j > 0) AT_PV(j - 1, vprev);
.LBB0_885:
	s_cmp_eq_u32 s92, 0
	s_cselect_b64 s[4:5], -1, 0
	s_or_b64 s[4:5], s[86:87], s[4:5]
	s_sub_i32 s6, s92, 64
	s_cmp_gt_i32 s6, s64
	s_cselect_b64 s[6:7], -1, 0
	s_or_b64 s[4:5], s[4:5], s[6:7]
	s_and_b64 vcc, exec, s[4:5]
	s_cbranch_vccnz .LBB0_893
	s_mulk_i32 s0, 0x4800
	v_add_u32_e32 v17, s0, v244
	v_max3_f32 v2, v98, v99, v100
	v_max3_f32 v4, v101, v102, v103
	v_max3_f32 v5, v104, v105, v106
	v_max3_f32 v6, v107, v108, v109
	v_max3_f32 v2, v2, v110, v111
	v_max3_f32 v4, v4, v112, v113
	v_max3_f32 v5, v5, v82, v83
	v_max3_f32 v6, v6, v84, v85
	v_max3_f32 v2, v2, v86, v87
	v_max3_f32 v4, v4, v88, v89
	v_max3_f32 v5, v5, v90, v91
	v_max3_f32 v6, v6, v92, v93
	v_max3_f32 v2, v2, v94, v95
	v_max3_f32 v4, v4, v96, v97
	v_max3_f32 v2, v2, v4, v5
	v_max_f32_e32 v2, v2, v6
	v_mov_b32_e32 v4, v2
	s_nop 1
	v_permlane32_swap_b32_e32 v2, v4
	v_max_f32_e32 v2, v2, v4
	v_sub_f32_e32 v4, v2, v252
	v_mul_f32_e32 v4, 0x3dd53b94, v4
	s_mov_b32 s0, 0x41380000
	v_cmp_ge_f32_e32 vcc, s0, v4
	s_cmp_eq_u64 vcc, exec
	s_cbranch_scc1 .Ld2_exp
	v_max_f32_e32 v2, v2, v2
	v_max_f32_e32 v4, v252, v252
	v_max_f32_e32 v4, v4, v2
	v_sub_f32_e32 v2, v252, v4
	v_mul_f32_e32 v2, 0x3dd53b94, v2
	v_exp_f32_e32 v2, v2
	v_mov_b32_e32 v252, v4
	v_pk_mul_f32 v[80:81], v[80:81], v[2:3] op_sel_hi:[1,0]
	v_pk_mul_f32 v[78:79], v[78:79], v[2:3] op_sel_hi:[1,0]
	v_pk_mul_f32 v[76:77], v[76:77], v[2:3] op_sel_hi:[1,0]
	v_pk_mul_f32 v[74:75], v[74:75], v[2:3] op_sel_hi:[1,0]
	v_pk_mul_f32 v[72:73], v[72:73], v[2:3] op_sel_hi:[1,0]
	v_pk_mul_f32 v[70:71], v[70:71], v[2:3] op_sel_hi:[1,0]
	v_pk_mul_f32 v[68:69], v[68:69], v[2:3] op_sel_hi:[1,0]
	v_pk_mul_f32 v[66:67], v[66:67], v[2:3] op_sel_hi:[1,0]
	v_pk_mul_f32 v[64:65], v[64:65], v[2:3] op_sel_hi:[1,0]
	v_pk_mul_f32 v[62:63], v[62:63], v[2:3] op_sel_hi:[1,0]
	v_pk_mul_f32 v[60:61], v[60:61], v[2:3] op_sel_hi:[1,0]
	v_pk_mul_f32 v[58:59], v[58:59], v[2:3] op_sel_hi:[1,0]
	v_pk_mul_f32 v[56:57], v[56:57], v[2:3] op_sel_hi:[1,0]
	v_pk_mul_f32 v[54:55], v[54:55], v[2:3] op_sel_hi:[1,0]
	v_pk_mul_f32 v[52:53], v[52:53], v[2:3] op_sel_hi:[1,0]
	v_pk_mul_f32 v[50:51], v[50:51], v[2:3] op_sel_hi:[1,0]
	v_pk_mul_f32 v[48:49], v[48:49], v[2:3] op_sel_hi:[1,0]
	v_pk_mul_f32 v[46:47], v[46:47], v[2:3] op_sel_hi:[1,0]
	v_pk_mul_f32 v[44:45], v[44:45], v[2:3] op_sel_hi:[1,0]
	v_pk_mul_f32 v[42:43], v[42:43], v[2:3] op_sel_hi:[1,0]
	v_pk_mul_f32 v[40:41], v[40:41], v[2:3] op_sel_hi:[1,0]
	v_pk_mul_f32 v[38:39], v[38:39], v[2:3] op_sel_hi:[1,0]
	v_pk_mul_f32 v[36:37], v[36:37], v[2:3] op_sel_hi:[1,0]
	v_pk_mul_f32 v[34:35], v[34:35], v[2:3] op_sel_hi:[1,0]
	v_pk_mul_f32 v[32:33], v[32:33], v[2:3] op_sel_hi:[1,0]
	v_pk_mul_f32 v[30:31], v[30:31], v[2:3] op_sel_hi:[1,0]
	v_pk_mul_f32 v[28:29], v[28:29], v[2:3] op_sel_hi:[1,0]
	v_pk_mul_f32 v[26:27], v[26:27], v[2:3] op_sel_hi:[1,0]
	v_pk_mul_f32 v[24:25], v[24:25], v[2:3] op_sel_hi:[1,0]
	v_pk_mul_f32 v[22:23], v[22:23], v[2:3] op_sel_hi:[1,0]
	v_pk_mul_f32 v[20:21], v[20:21], v[2:3] op_sel_hi:[1,0]
	v_pk_mul_f32 v[18:19], v[18:19], v[2:3] op_sel_hi:[1,0]
	v_mul_f32_e32 v250, v250, v2

; template <int DQK, bool CAUSAL, bool ROPE> ...
;     ...
;     if (grp == 1) AT_PV(ntiles - 1, vprev);
.LBB0_899:
	s_and_b64 vcc, exec, s[88:89]
	s_cbranch_vccz .LBB0_881
	s_lshl_b32 s0, s33, 6
	s_sub_i32 s0, s0, 64
	s_cmp_gt_i32 s0, s64
	s_cbranch_scc1 .LBB0_881
	s_mul_i32 s0, s71, 0x4800
	v_add_u32_e32 v17, s0, v244
	v_max3_f32 v2, v98, v99, v100
	v_max3_f32 v4, v101, v102, v103
	v_max3_f32 v5, v104, v105, v106
	v_max3_f32 v6, v107, v108, v109
	v_max3_f32 v2, v2, v110, v111
	v_max3_f32 v4, v4, v112, v113
	v_max3_f32 v5, v5, v82, v83
	v_max3_f32 v6, v6, v84, v85
	v_max3_f32 v2, v2, v86, v87
	v_max3_f32 v4, v4, v88, v89
	v_max3_f32 v5, v5, v90, v91
	v_max3_f32 v6, v6, v92, v93
	v_max3_f32 v2, v2, v94, v95
	v_max3_f32 v4, v4, v96, v97
	v_max3_f32 v2, v2, v4, v5
	v_max_f32_e32 v2, v2, v6
	v_mov_b32_e32 v4, v2
	s_nop 1
	v_permlane32_swap_b32_e32 v2, v4
	v_max_f32_e32 v2, v2, v4
	v_sub_f32_e32 v4, v2, v252
	v_mul_f32_e32 v4, 0x3dd53b94, v4
	s_mov_b32 s0, 0x41380000
	v_cmp_ge_f32_e32 vcc, s0, v4
	s_cmp_eq_u64 vcc, exec
	s_cbranch_scc1 .Ld3_exp
	v_max_f32_e32 v2, v2, v2
	v_max_f32_e32 v4, v252, v252
	v_max_f32_e32 v4, v4, v2
	v_sub_f32_e32 v2, v252, v4
	v_mul_f32_e32 v2, 0x3dd53b94, v2
	v_exp_f32_e32 v2, v2
	v_mov_b32_e32 v252, v4
	v_pk_mul_f32 v[80:81], v[80:81], v[2:3] op_sel_hi:[1,0]
	v_pk_mul_f32 v[78:79], v[78:79], v[2:3] op_sel_hi:[1,0]
	v_pk_mul_f32 v[76:77], v[76:77], v[2:3] op_sel_hi:[1,0]
	v_pk_mul_f32 v[74:75], v[74:75], v[2:3] op_sel_hi:[1,0]
	v_pk_mul_f32 v[72:73], v[72:73], v[2:3] op_sel_hi:[1,0]
	v_pk_mul_f32 v[70:71], v[70:71], v[2:3] op_sel_hi:[1,0]
	v_pk_mul_f32 v[68:69], v[68:69], v[2:3] op_sel_hi:[1,0]
	v_pk_mul_f32 v[66:67], v[66:67], v[2:3] op_sel_hi:[1,0]
	v_pk_mul_f32 v[64:65], v[64:65], v[2:3] op_sel_hi:[1,0]
	v_pk_mul_f32 v[62:63], v[62:63], v[2:3] op_sel_hi:[1,0]
	v_pk_mul_f32 v[60:61], v[60:61], v[2:3] op_sel_hi:[1,0]
	v_pk_mul_f32 v[58:59], v[58:59], v[2:3] op_sel_hi:[1,0]
	v_pk_mul_f32 v[56:57], v[56:57], v[2:3] op_sel_hi:[1,0]
	v_pk_mul_f32 v[54:55], v[54:55], v[2:3] op_sel_hi:[1,0]
	v_pk_mul_f32 v[52:53], v[52:53], v[2:3] op_sel_hi:[1,0]
	v_pk_mul_f32 v[50:51], v[50:51], v[2:3] op_sel_hi:[1,0]
	v_pk_mul_f32 v[48:49], v[48:49], v[2:3] op_sel_hi:[1,0]
	v_pk_mul_f32 v[46:47], v[46:47], v[2:3] op_sel_hi:[1,0]
	v_pk_mul_f32 v[44:45], v[44:45], v[2:3] op_sel_hi:[1,0]
	v_pk_mul_f32 v[42:43], v[42:43], v[2:3] op_sel_hi:[1,0]
	v_pk_mul_f32 v[40:41], v[40:41], v[2:3] op_sel_hi:[1,0]
	v_pk_mul_f32 v[38:39], v[38:39], v[2:3] op_sel_hi:[1,0]
	v_pk_mul_f32 v[36:37], v[36:37], v[2:3] op_sel_hi:[1,0]
	v_pk_mul_f32 v[34:35], v[34:35], v[2:3] op_sel_hi:[1,0]
	v_pk_mul_f32 v[32:33], v[32:33], v[2:3] op_sel_hi:[1,0]
	v_pk_mul_f32 v[30:31], v[30:31], v[2:3] op_sel_hi:[1,0]
	v_pk_mul_f32 v[28:29], v[28:29], v[2:3] op_sel_hi:[1,0]
	v_pk_mul_f32 v[26:27], v[26:27], v[2:3] op_sel_hi:[1,0]
	v_pk_mul_f32 v[24:25], v[24:25], v[2:3] op_sel_hi:[1,0]
	v_pk_mul_f32 v[22:23], v[22:23], v[2:3] op_sel_hi:[1,0]
	v_pk_mul_f32 v[20:21], v[20:21], v[2:3] op_sel_hi:[1,0]
	v_pk_mul_f32 v[18:19], v[18:19], v[2:3] op_sel_hi:[1,0]
	v_mul_f32_e32 v250, v250, v2
